# adds: P5 conv_row staging loads issued together with counted waits (was 8 serialized load-wait-ds_write round trips); gain hoist in P0 rms loop
# speedup vs baseline: 1.0720x; 1.0085x over previous
; DI unsigned pk2(float lo, float hi) { f32x2_t v = {lo, hi}; bf16x2_t b = __builtin_convertvector(v, bf16x2_t); return __builtin_bit_cast(unsigned, b); }
; template <int NR> DI void rms_rows_to_bf16(const float* x, const float* g, bf16* o, int m0, int mstride, int lane) {
;     f32x4 v[NR][4]; float s[NR];
; #pragma unroll
;     for (int r = 0; r < NR; ++r)
; #pragma unroll
;         for (int j = 0; j < 4; ++j) v[r][j] = __builtin_nontemporal_load((const f32x4*)(x + (size_t)(m0 + r * mstride) * DM + 4 * lane + 256 * j));
; #pragma unroll
;     for (int r = 0; r < NR; ++r) { s[r] = 0.f;
; #pragma unroll
;         for (int j = 0; j < 4; ++j) s[r] += (v[r][j][0] * v[r][j][0] + v[r][j][1] * v[r][j][1]) + (v[r][j][2] * v[r][j][2] + v[r][j][3] * v[r][j][3]); }
; #pragma unroll
;     for (int r = 0; r < NR; ++r) {
;         const float rr = rsqrtf(wave_sum(s[r]) * (1.f / 1024.f) + EPS);
; #pragma unroll
;         for (int j = 0; j < 4; ++j) { const f32x4 gg = *(const f32x4*)(g + 4 * lane + 256 * j); const f32x4 ov = v[r][j] * rr * gg;
;             u32x2 w; w.x = pk2(ov[0], ov[1]); w.y = pk2(ov[2], ov[3]); *(u32x2*)(o + (size_t)(m0 + r * mstride) * DM + 4 * lane + 256 * j) = w; }
;     }
; }
; __global__ void __launch_bounds__(512, 2) mk_fwd(Args a) {
;     ...
;         for (int m = gw; m < M; m += 4 * NGW) rms_rows_to_bf16<4>(x, (const float*)a.in[2], P, m, NGW, lane);
.LBB0_230:
	s_or_b64 exec, exec, s[0:1]
	s_cmpk_gt_i32 s58, 0x7fff
	s_cbranch_scc1 .LBB0_233
	v_readlane_b32 s12, v253, 3
	v_lshlrev_b32_e32 v0, 4, v196
	v_mov_b32_e32 v1, 0
	v_readlane_b32 s13, v253, 4
	v_readlane_b32 s16, v253, 7
	v_readlane_b32 s17, v253, 8
	v_readlane_b32 s0, v253, 45
	v_lshl_add_u64 v[56:57], s[12:13], 0, v[0:1]
	v_lshl_add_u64 v[58:59], s[16:17], 0, v[0:1]
	v_lshlrev_b32_e32 v0, 3, v196
	v_readlane_b32 s1, v253, 46
	s_mov_b32 s4, 0x358637bd
	v_mov_b64_e32 v[62:63], s[4:5]
	v_lshl_add_u64 v[60:61], s[0:1], 0, v[0:1]
	v_mbcnt_lo_u32_b32 v0, -1, 0
	v_mbcnt_hi_u32_b32 v0, -1, v0
	v_and_b32_e32 v1, 64, v0
	v_add_u32_e32 v1, 64, v1
	v_xor_b32_e32 v2, 1, v0
	v_cmp_lt_i32_e32 vcc, v2, v1
	v_readlane_b32 s0, v253, 1
	v_readlane_b32 s1, v253, 2
	v_cndmask_b32_e32 v2, v0, v2, vcc
	v_lshlrev_b32_e32 v64, 2, v2
	v_xor_b32_e32 v2, 2, v0
	v_cmp_lt_i32_e32 vcc, v2, v1
	s_lshl_b32 s1, s0, 4
	s_mul_i32 s16, s0, 24
	v_cndmask_b32_e32 v2, v0, v2, vcc
	v_lshlrev_b32_e32 v65, 2, v2
	v_xor_b32_e32 v2, 4, v0
	v_cmp_lt_i32_e32 vcc, v2, v1
	s_mov_b32 s0, 0x3a800000
	s_mov_b32 s17, 0x800000
	v_cndmask_b32_e32 v2, v0, v2, vcc
	v_lshlrev_b32_e32 v66, 2, v2
	v_xor_b32_e32 v2, 8, v0
	v_cmp_lt_i32_e32 vcc, v2, v1
	s_mov_b32 s12, s58
	v_readlane_b32 s14, v253, 5
	v_cndmask_b32_e32 v2, v0, v2, vcc
	v_lshlrev_b32_e32 v67, 2, v2
	v_xor_b32_e32 v2, 16, v0
	v_cmp_lt_i32_e32 vcc, v2, v1
	v_readlane_b32 s15, v253, 6
	v_readlane_b32 s18, v253, 9
	v_cndmask_b32_e32 v2, v0, v2, vcc
	v_lshlrev_b32_e32 v68, 2, v2
	v_xor_b32_e32 v2, 32, v0
	v_cmp_lt_i32_e32 vcc, v2, v1
	v_readlane_b32 s19, v253, 10
	v_readlane_b32 s20, v253, 11
	v_cndmask_b32_e32 v0, v0, v2, vcc
	v_lshlrev_b32_e32 v69, 2, v0
	v_readlane_b32 s21, v253, 12
	v_readlane_b32 s22, v253, 13
	v_readlane_b32 s23, v253, 14
	v_readlane_b32 s24, v253, 15
	v_readlane_b32 s25, v253, 16
	v_readlane_b32 s26, v253, 17
	v_readlane_b32 s27, v253, 18
	global_load_dwordx4 v[200:203], v[58:59], off
	global_load_dwordx4 v[204:207], v[58:59], off offset:1024
	global_load_dwordx4 v[208:211], v[58:59], off offset:2048
	global_load_dwordx4 v[212:215], v[58:59], off offset:3072
	s_waitcnt vmcnt(0)
.LBB0_232:
	s_ashr_i32 s13, s12, 31
	s_lshl_b64 s[4:5], s[12:13], 12
	v_lshl_add_u64 v[0:1], v[56:57], 0, s[4:5]
	global_load_dwordx4 v[32:35], v[0:1], off nt
	global_load_dwordx4 v[28:31], v[0:1], off offset:1024 nt
	global_load_dwordx4 v[16:19], v[0:1], off offset:3072 nt
	global_load_dwordx4 v[20:23], v[0:1], off offset:2048 nt
	s_add_i32 s4, s12, s68
	s_ashr_i32 s5, s4, 31
	s_lshl_b64 s[10:11], s[4:5], 12
	v_lshl_add_u64 v[4:5], v[56:57], 0, s[10:11]
	global_load_dwordx4 v[12:15], v[4:5], off nt
	global_load_dwordx4 v[8:11], v[4:5], off offset:1024 nt
	global_load_dwordx4 v[0:3], v[4:5], off offset:3072 nt
	s_nop 0
	global_load_dwordx4 v[4:7], v[4:5], off offset:2048 nt
	s_nop 0
	global_load_dwordx4 v[70:73], v[58:59], off
	s_add_i32 s14, s1, s12
	s_add_i32 s10, s16, s12
	s_ashr_i32 s15, s14, 31
	s_ashr_i32 s11, s10, 31
	s_lshl_b64 s[18:19], s[14:15], 12
	s_lshl_b64 s[20:21], s[10:11], 12
	v_lshl_add_u64 v[84:85], v[56:57], 0, s[20:21]
	s_lshl_b64 s[12:13], s[12:13], 11
	v_lshl_add_u64 v[82:83], v[60:61], 0, s[12:13]
	s_lshl_b64 s[12:13], s[4:5], 11
	s_lshl_b64 s[10:11], s[10:11], 11
	s_add_i32 s4, s4, s68
	s_add_i32 s4, s4, s68
	s_waitcnt vmcnt(8)
	v_pk_mul_f32 v[24:25], v[34:35], v[34:35]
	v_pk_mul_f32 v[26:27], v[32:33], v[32:33]
	s_waitcnt vmcnt(7)
	v_pk_mul_f32 v[36:37], v[30:31], v[30:31]
	v_pk_mul_f32 v[38:39], v[28:29], v[28:29]
	s_waitcnt vmcnt(5)
	v_mul_f32_e32 v40, v21, v21
	v_mul_f32_e32 v42, v23, v23
	v_mul_f32_e32 v74, v18, v18
	v_mul_f32_e32 v75, v19, v19
	v_pk_mov_b32 v[44:45], v[26:27], v[24:25] op_sel:[1,0]
	v_mov_b32_e32 v27, v25
	v_pk_mov_b32 v[24:25], v[38:39], v[36:37] op_sel:[1,0]
	v_mov_b32_e32 v39, v37
	v_pk_fma_f32 v[36:37], v[20:21], v[20:21], v[40:41] op_sel_hi:[1,1,0]
	v_pk_fma_f32 v[40:41], v[22:23], v[22:23], v[42:43] op_sel_hi:[1,1,0]
	s_waitcnt vmcnt(4)
	v_pk_mul_f32 v[42:43], v[14:15], v[14:15]
	v_pk_mul_f32 v[46:47], v[12:13], v[12:13]
	s_waitcnt vmcnt(3)
	v_pk_mul_f32 v[48:49], v[10:11], v[10:11]
	v_pk_mul_f32 v[50:51], v[8:9], v[8:9]
	v_pk_add_f32 v[24:25], v[24:25], v[38:39]
	v_mov_b32_e32 v37, v74
	v_mov_b32_e32 v41, v75
	v_pk_mov_b32 v[38:39], v[46:47], v[42:43] op_sel:[1,0]
	v_mov_b32_e32 v47, v43
	v_pk_mov_b32 v[42:43], v[50:51], v[48:49] op_sel:[1,0]
	v_mov_b32_e32 v51, v49
	v_mul_f32_e32 v53, v16, v16
	v_mul_f32_e32 v55, v17, v17
	s_waitcnt vmcnt(1)
	v_mul_f32_e32 v52, v5, v5
	v_mul_f32_e32 v54, v7, v7
	v_pk_add_f32 v[26:27], v[44:45], v[26:27]
	v_pk_add_f32 v[36:37], v[36:37], v[40:41]
	v_pk_add_f32 v[38:39], v[38:39], v[46:47]
	v_pk_add_f32 v[40:41], v[42:43], v[50:51]
	v_mul_f32_e32 v76, v0, v0
	v_mul_f32_e32 v77, v1, v1
	v_mul_f32_e32 v78, v2, v2
	v_mul_f32_e32 v79, v3, v3
	v_pk_fma_f32 v[44:45], v[4:5], v[4:5], v[52:53] op_sel_hi:[1,1,0]
	v_pk_fma_f32 v[48:49], v[6:7], v[6:7], v[54:55] op_sel_hi:[1,1,0]
	v_pk_add_f32 v[26:27], v[26:27], v[26:27] op_sel:[0,1] op_sel_hi:[1,0]
	v_pk_add_f32 v[24:25], v[24:25], v[24:25] op_sel:[0,1] op_sel_hi:[1,0]
	v_pk_add_f32 v[38:39], v[38:39], v[38:39] op_sel:[0,1] op_sel_hi:[1,0]
	v_pk_add_f32 v[40:41], v[40:41], v[40:41] op_sel:[0,1] op_sel_hi:[1,0]
	v_mov_b32_e32 v45, v78
	v_mov_b32_e32 v49, v79
	v_mov_b32_e32 v27, v53
	v_mov_b32_e32 v25, v55
	v_mov_b32_e32 v39, v76
	v_mov_b32_e32 v41, v77
	v_pk_add_f32 v[42:43], v[44:45], v[48:49]
	v_pk_add_f32 v[24:25], v[26:27], v[24:25]
	v_pk_add_f32 v[26:27], v[38:39], v[40:41]
	v_pk_add_f32 v[24:25], v[24:25], v[36:37]
	v_pk_add_f32 v[26:27], v[26:27], v[42:43]
	v_mov_b32_e32 v37, v24
	v_mov_b32_e32 v36, v26
	v_mov_b32_e32 v24, v27
	v_pk_add_f32 v[24:25], v[36:37], v[24:25]
	ds_bpermute_b32 v27, v64, v25
	ds_bpermute_b32 v26, v64, v24
	v_lshl_add_u64 v[36:37], v[56:57], 0, s[18:19]
	global_load_dwordx4 v[74:77], v[36:37], off nt
	global_load_dwordx4 v[78:81], v[36:37], off offset:1024 nt
	global_load_dwordx4 v[52:55], v[36:37], off offset:2048 nt
	global_load_dwordx4 v[48:51], v[36:37], off offset:3072 nt
	s_waitcnt lgkmcnt(0)
; DI unsigned pk2(float lo, float hi) { f32x2_t v = {lo, hi}; bf16x2_t b = __builtin_convertvector(v, bf16x2_t); return __builtin_bit_cast(unsigned, b); }
; template <int NR> DI void rms_rows_to_bf16(const float* x, const float* g, bf16* o, int m0, int mstride, int lane) {
;     f32x4 v[NR][4]; float s[NR];
; #pragma unroll
;     for (int r = 0; r < NR; ++r)
; #pragma unroll
;         for (int j = 0; j < 4; ++j) v[r][j] = __builtin_nontemporal_load((const f32x4*)(x + (size_t)(m0 + r * mstride) * DM + 4 * lane + 256 * j));
; #pragma unroll
;     for (int r = 0; r < NR; ++r) { s[r] = 0.f;
; #pragma unroll
;         for (int j = 0; j < 4; ++j) s[r] += (v[r][j][0] * v[r][j][0] + v[r][j][1] * v[r][j][1]) + (v[r][j][2] * v[r][j][2] + v[r][j][3] * v[r][j][3]); }
; #pragma unroll
;     for (int r = 0; r < NR; ++r) {
;         const float rr = rsqrtf(wave_sum(s[r]) * (1.f / 1024.f) + EPS);
; #pragma unroll
;         for (int j = 0; j < 4; ++j) { const f32x4 gg = *(const f32x4*)(g + 4 * lane + 256 * j); const f32x4 ov = v[r][j] * rr * gg;
;             u32x2 w; w.x = pk2(ov[0], ov[1]); w.y = pk2(ov[2], ov[3]); *(u32x2*)(o + (size_t)(m0 + r * mstride) * DM + 4 * lane + 256 * j) = w; }
;     }
; }
	v_pk_add_f32 v[24:25], v[24:25], v[26:27]
	ds_bpermute_b32 v27, v65, v25
	ds_bpermute_b32 v26, v65, v24
	s_waitcnt lgkmcnt(0)
	v_pk_add_f32 v[24:25], v[24:25], v[26:27]
	ds_bpermute_b32 v27, v66, v25
	ds_bpermute_b32 v26, v66, v24
	s_waitcnt lgkmcnt(0)
	v_pk_add_f32 v[24:25], v[24:25], v[26:27]
	ds_bpermute_b32 v27, v67, v25
	ds_bpermute_b32 v26, v67, v24
	s_waitcnt lgkmcnt(0)
	v_pk_add_f32 v[24:25], v[24:25], v[26:27]
	ds_bpermute_b32 v27, v68, v25
	ds_bpermute_b32 v26, v68, v24
	s_waitcnt lgkmcnt(0)
	v_pk_add_f32 v[24:25], v[24:25], v[26:27]
	ds_bpermute_b32 v27, v69, v25
	ds_bpermute_b32 v26, v69, v24
	s_waitcnt lgkmcnt(0)
	v_pk_add_f32 v[24:25], v[24:25], v[26:27]
	s_nop 0
	v_pk_fma_f32 v[86:87], v[24:25], s[0:1], v[62:63] op_sel_hi:[1,0,0]
	s_nop 0
	v_mul_f32_e32 v24, 0x4b800000, v87
	v_cmp_gt_f32_e32 vcc, s17, v87
	s_nop 1
	v_cndmask_b32_e32 v24, v87, v24, vcc
	v_rsq_f32_e32 v87, v24
	global_load_dwordx4 v[44:47], v[84:85], off nt
	global_load_dwordx4 v[40:43], v[84:85], off offset:1024 nt
	global_load_dwordx4 v[36:39], v[84:85], off offset:2048 nt
	global_load_dwordx4 v[24:27], v[84:85], off offset:3072 nt
	v_mul_f32_e32 v84, 0x45800000, v87
	v_cndmask_b32_e32 v84, v87, v84, vcc
	v_pk_mul_f32 v[32:33], v[32:33], v[84:85] op_sel_hi:[1,0]
	v_pk_mul_f32 v[34:35], v[34:35], v[84:85] op_sel_hi:[1,0]
	s_waitcnt vmcnt(8)
	v_pk_mul_f32 v[32:33], v[70:71], v[32:33]
	v_pk_mul_f32 v[34:35], v[72:73], v[34:35]
	v_cvt_pk_bf16_f32 v32, v32, v33
	v_cvt_pk_bf16_f32 v33, v34, v35
	global_store_dwordx2 v[82:83], v[32:33], off
	global_load_dwordx4 v[32:35], v[58:59], off offset:1024
	v_pk_mul_f32 v[28:29], v[28:29], v[84:85] op_sel_hi:[1,0]
	v_pk_mul_f32 v[30:31], v[30:31], v[84:85] op_sel_hi:[1,0]
	v_pk_mul_f32 v[20:21], v[20:21], v[84:85] op_sel_hi:[1,0]
	v_pk_mul_f32 v[22:23], v[22:23], v[84:85] op_sel_hi:[1,0]
	v_pk_mul_f32 v[16:17], v[16:17], v[84:85] op_sel_hi:[1,0]
	v_pk_mul_f32 v[18:19], v[18:19], v[84:85] op_sel_hi:[1,0]
	v_cmp_gt_f32_e32 vcc, s17, v86
	s_waitcnt vmcnt(6)
	v_mul_f32_e32 v73, v49, v49
	v_mul_f32_e32 v84, v50, v50
	v_mul_f32_e32 v85, v51, v51
	s_waitcnt vmcnt(3)
	v_mul_f32_e32 v70, v37, v37
	v_mul_f32_e32 v72, v39, v39
	s_waitcnt vmcnt(2)
	v_mul_f32_e32 v87, v25, v25
	v_mul_f32_e32 v88, v26, v26
	v_mul_f32_e32 v89, v27, v27
	s_waitcnt vmcnt(0)
	v_pk_mul_f32 v[30:31], v[34:35], v[30:31]
	v_pk_mul_f32 v[28:29], v[32:33], v[28:29]
	v_pk_mul_f32 v[32:33], v[42:43], v[42:43]
	v_cvt_pk_bf16_f32 v28, v28, v29
	v_cvt_pk_bf16_f32 v29, v30, v31
	global_store_dwordx2 v[82:83], v[28:29], off offset:512
	s_nop 1
	v_mov_b64_e32 v[28:29], v[208:209]
	v_mov_b64_e32 v[30:31], v[210:211]
	v_pk_mul_f32 v[34:35], v[40:41], v[40:41]
	s_nop 1
	v_pk_mul_f32 v[22:23], v[30:31], v[22:23]
	v_pk_mul_f32 v[20:21], v[28:29], v[20:21]
	v_pk_mul_f32 v[28:29], v[46:47], v[46:47]
	v_cvt_pk_bf16_f32 v20, v20, v21
	v_cvt_pk_bf16_f32 v21, v22, v23
	global_store_dwordx2 v[82:83], v[20:21], off offset:1024
	s_nop 1
	v_mov_b64_e32 v[20:21], v[212:213]
	v_mov_b64_e32 v[22:23], v[214:215]
	v_pk_mul_f32 v[30:31], v[44:45], v[44:45]
	s_nop 1
	v_pk_mul_f32 v[18:19], v[22:23], v[18:19]
	v_pk_mul_f32 v[16:17], v[20:21], v[16:17]
	v_mul_f32_e32 v20, 0x4b800000, v86
	v_cvt_pk_bf16_f32 v16, v16, v17
	v_cvt_pk_bf16_f32 v17, v18, v19
	global_store_dwordx2 v[82:83], v[16:17], off offset:1536
	s_nop 1
	v_mov_b64_e32 v[16:17], v[200:201]
	v_mov_b64_e32 v[18:19], v[202:203]
	v_cndmask_b32_e32 v20, v86, v20, vcc
	v_rsq_f32_e32 v22, v20
	v_lshl_add_u64 v[20:21], v[60:61], 0, s[12:13]
	v_mul_f32_e32 v86, v24, v24
	s_lshl_b64 s[12:13], s[14:15], 11
	v_mul_f32_e32 v23, 0x45800000, v22
	v_cndmask_b32_e32 v22, v22, v23, vcc
	v_pk_mul_f32 v[12:13], v[12:13], v[22:23] op_sel_hi:[1,0]
	v_pk_mul_f32 v[14:15], v[14:15], v[22:23] op_sel_hi:[1,0]
	v_pk_mul_f32 v[8:9], v[8:9], v[22:23] op_sel_hi:[1,0]
	v_pk_mul_f32 v[10:11], v[10:11], v[22:23] op_sel_hi:[1,0]
	v_pk_mul_f32 v[4:5], v[4:5], v[22:23] op_sel_hi:[1,0]
	v_pk_mul_f32 v[6:7], v[6:7], v[22:23] op_sel_hi:[1,0]
	v_mul_f32_e32 v23, v48, v48
	v_pk_mul_f32 v[0:1], v[0:1], v[22:23] op_sel_hi:[1,0]
	v_pk_mul_f32 v[2:3], v[2:3], v[22:23] op_sel_hi:[1,0]
	s_nop 1
	v_pk_mul_f32 v[14:15], v[18:19], v[14:15]
	v_pk_mul_f32 v[12:13], v[16:17], v[12:13]
	v_mul_f32_e32 v16, v53, v53
	v_cvt_pk_bf16_f32 v12, v12, v13
	v_cvt_pk_bf16_f32 v13, v14, v15
	global_store_dwordx2 v[20:21], v[12:13], off
	s_nop 1
	v_mov_b64_e32 v[12:13], v[204:205]
	v_mov_b64_e32 v[14:15], v[206:207]
	v_mul_f32_e32 v18, v55, v55
	s_nop 1
	v_pk_mul_f32 v[10:11], v[14:15], v[10:11]
	v_pk_mul_f32 v[8:9], v[12:13], v[8:9]
	v_pk_mul_f32 v[12:13], v[80:81], v[80:81]
	v_cvt_pk_bf16_f32 v8, v8, v9
	v_cvt_pk_bf16_f32 v9, v10, v11
	global_store_dwordx2 v[20:21], v[8:9], off offset:512
	s_nop 1
	v_mov_b64_e32 v[8:9], v[208:209]
	v_mov_b64_e32 v[10:11], v[210:211]
	v_pk_mul_f32 v[14:15], v[78:79], v[78:79]
	s_nop 1
	v_pk_mul_f32 v[6:7], v[10:11], v[6:7]
	v_pk_mul_f32 v[4:5], v[8:9], v[4:5]
	v_pk_mul_f32 v[8:9], v[76:77], v[76:77]
	v_cvt_pk_bf16_f32 v4, v4, v5
	v_cvt_pk_bf16_f32 v5, v6, v7
	global_store_dwordx2 v[20:21], v[4:5], off offset:1024
	s_nop 1
	v_mov_b64_e32 v[4:5], v[212:213]
	v_mov_b64_e32 v[6:7], v[214:215]
	v_pk_mul_f32 v[10:11], v[74:75], v[74:75]
	s_nop 1
	v_pk_mul_f32 v[2:3], v[6:7], v[2:3]
	v_pk_mul_f32 v[0:1], v[4:5], v[0:1]
	v_pk_mov_b32 v[82:83], v[10:11], v[8:9] op_sel:[1,0]
	v_cvt_pk_bf16_f32 v0, v0, v1
	v_cvt_pk_bf16_f32 v1, v2, v3
	global_store_dwordx2 v[20:21], v[0:1], off offset:1536
	s_nop 1
	v_mov_b64_e32 v[0:1], v[200:201]
	v_mov_b64_e32 v[2:3], v[202:203]
	v_mov_b32_e32 v11, v9
	v_pk_mov_b32 v[8:9], v[14:15], v[12:13] op_sel:[1,0]
	v_mov_b32_e32 v15, v13
; DI unsigned pk2(float lo, float hi) { f32x2_t v = {lo, hi}; bf16x2_t b = __builtin_convertvector(v, bf16x2_t); return __builtin_bit_cast(unsigned, b); }
; template <int NR> DI void rms_rows_to_bf16(const float* x, const float* g, bf16* o, int m0, int mstride, int lane) {
;     f32x4 v[NR][4]; float s[NR];
; #pragma unroll
;     for (int r = 0; r < NR; ++r)
; #pragma unroll
;         for (int j = 0; j < 4; ++j) v[r][j] = __builtin_nontemporal_load((const f32x4*)(x + (size_t)(m0 + r * mstride) * DM + 4 * lane + 256 * j));
; #pragma unroll
;     for (int r = 0; r < NR; ++r) { s[r] = 0.f;
; #pragma unroll
;         for (int j = 0; j < 4; ++j) s[r] += (v[r][j][0] * v[r][j][0] + v[r][j][1] * v[r][j][1]) + (v[r][j][2] * v[r][j][2] + v[r][j][3] * v[r][j][3]); }
; #pragma unroll
;     for (int r = 0; r < NR; ++r) {
;         const float rr = rsqrtf(wave_sum(s[r]) * (1.f / 1024.f) + EPS);
; #pragma unroll
;         for (int j = 0; j < 4; ++j) { const f32x4 gg = *(const f32x4*)(g + 4 * lane + 256 * j); const f32x4 ov = v[r][j] * rr * gg;
;             u32x2 w; w.x = pk2(ov[0], ov[1]); w.y = pk2(ov[2], ov[3]); *(u32x2*)(o + (size_t)(m0 + r * mstride) * DM + 4 * lane + 256 * j) = w; }
;     }
; }
	v_pk_fma_f32 v[12:13], v[52:53], v[52:53], v[16:17] op_sel_hi:[1,1,0]
	v_pk_fma_f32 v[16:17], v[54:55], v[54:55], v[18:19] op_sel_hi:[1,1,0]
	v_pk_mov_b32 v[18:19], v[30:31], v[28:29] op_sel:[1,0]
	v_mov_b32_e32 v31, v29
	v_pk_mov_b32 v[28:29], v[34:35], v[32:33] op_sel:[1,0]
	v_mov_b32_e32 v35, v33
	v_pk_add_f32 v[10:11], v[82:83], v[10:11]
	v_pk_add_f32 v[4:5], v[8:9], v[14:15]
	v_pk_add_f32 v[6:7], v[18:19], v[30:31]
	v_pk_add_f32 v[8:9], v[28:29], v[34:35]
	v_pk_fma_f32 v[32:33], v[36:37], v[36:37], v[70:71] op_sel_hi:[1,1,0]
	v_pk_fma_f32 v[70:71], v[38:39], v[38:39], v[72:73] op_sel_hi:[1,1,0]
	v_pk_add_f32 v[10:11], v[10:11], v[10:11] op_sel:[0,1] op_sel_hi:[1,0]
	v_pk_add_f32 v[4:5], v[4:5], v[4:5] op_sel:[0,1] op_sel_hi:[1,0]
	v_pk_add_f32 v[6:7], v[6:7], v[6:7] op_sel:[0,1] op_sel_hi:[1,0]
	v_pk_add_f32 v[8:9], v[8:9], v[8:9] op_sel:[0,1] op_sel_hi:[1,0]
	v_mov_b32_e32 v13, v84
	v_mov_b32_e32 v17, v85
	v_mov_b32_e32 v33, v88
	v_mov_b32_e32 v71, v89
	v_mov_b32_e32 v11, v23
	v_mov_b32_e32 v5, v73
	v_mov_b32_e32 v7, v86
	v_mov_b32_e32 v9, v87
	v_pk_add_f32 v[12:13], v[12:13], v[16:17]
	v_pk_add_f32 v[14:15], v[32:33], v[70:71]
	v_pk_add_f32 v[4:5], v[10:11], v[4:5]
	v_pk_add_f32 v[6:7], v[6:7], v[8:9]
	v_pk_add_f32 v[4:5], v[4:5], v[12:13]
	v_pk_add_f32 v[6:7], v[6:7], v[14:15]
	v_mov_b32_e32 v9, v4
	v_mov_b32_e32 v8, v6
	v_mov_b32_e32 v4, v7
	v_pk_add_f32 v[4:5], v[8:9], v[4:5]
	ds_bpermute_b32 v7, v64, v5
	ds_bpermute_b32 v6, v64, v4
	s_waitcnt lgkmcnt(0)
	v_pk_add_f32 v[4:5], v[4:5], v[6:7]
	ds_bpermute_b32 v7, v65, v5
	ds_bpermute_b32 v6, v65, v4
	s_waitcnt lgkmcnt(0)
	v_pk_add_f32 v[4:5], v[4:5], v[6:7]
	ds_bpermute_b32 v7, v66, v5
	ds_bpermute_b32 v6, v66, v4
	s_waitcnt lgkmcnt(0)
	v_pk_add_f32 v[4:5], v[4:5], v[6:7]
	ds_bpermute_b32 v7, v67, v5
	ds_bpermute_b32 v6, v67, v4
	s_waitcnt lgkmcnt(0)
	v_pk_add_f32 v[4:5], v[4:5], v[6:7]
	ds_bpermute_b32 v7, v68, v5
	ds_bpermute_b32 v6, v68, v4
	s_waitcnt lgkmcnt(0)
	v_pk_add_f32 v[4:5], v[4:5], v[6:7]
	ds_bpermute_b32 v7, v69, v5
	ds_bpermute_b32 v6, v69, v4
	s_waitcnt lgkmcnt(0)
	v_pk_add_f32 v[4:5], v[4:5], v[6:7]
	s_nop 0
	v_pk_fma_f32 v[4:5], v[4:5], s[0:1], v[62:63] op_sel_hi:[1,0,0]
	s_nop 0
	v_mul_f32_e32 v6, 0x4b800000, v5
	v_cmp_gt_f32_e32 vcc, s17, v5
	s_nop 1
	v_cndmask_b32_e32 v5, v5, v6, vcc
	v_rsq_f32_e32 v5, v5
	v_lshl_add_u64 v[6:7], v[60:61], 0, s[12:13]
	s_add_i32 s12, s4, s68
	s_cmp_lt_i32 s12, 0x8000
	v_mul_f32_e32 v8, 0x45800000, v5
	v_cndmask_b32_e32 v8, v5, v8, vcc
	v_pk_mul_f32 v[10:11], v[74:75], v[8:9] op_sel_hi:[1,0]
	v_pk_mul_f32 v[12:13], v[76:77], v[8:9] op_sel_hi:[1,0]
	s_nop 1
	v_pk_mul_f32 v[0:1], v[0:1], v[10:11]
	v_pk_mul_f32 v[2:3], v[2:3], v[12:13]
	v_cvt_pk_bf16_f32 v0, v0, v1
	v_cvt_pk_bf16_f32 v1, v2, v3
	global_store_dwordx2 v[6:7], v[0:1], off
	s_nop 1
	v_mov_b64_e32 v[0:1], v[204:205]
	v_mov_b64_e32 v[2:3], v[206:207]
	v_pk_mul_f32 v[10:11], v[78:79], v[8:9] op_sel_hi:[1,0]
	v_pk_mul_f32 v[12:13], v[80:81], v[8:9] op_sel_hi:[1,0]
	v_mul_f32_e32 v5, 0x4b800000, v4
	v_cmp_gt_f32_e32 vcc, s17, v4
	s_nop 1
	v_pk_mul_f32 v[2:3], v[2:3], v[12:13]
	v_pk_mul_f32 v[0:1], v[0:1], v[10:11]
	v_pk_mul_f32 v[10:11], v[52:53], v[8:9] op_sel_hi:[1,0]
	v_cvt_pk_bf16_f32 v0, v0, v1
	v_cvt_pk_bf16_f32 v1, v2, v3
	global_store_dwordx2 v[6:7], v[0:1], off offset:512
	s_nop 1
	v_mov_b64_e32 v[0:1], v[208:209]
	v_mov_b64_e32 v[2:3], v[210:211]
	v_pk_mul_f32 v[12:13], v[54:55], v[8:9] op_sel_hi:[1,0]
	v_cndmask_b32_e32 v4, v4, v5, vcc
	s_nop 1
	v_pk_mul_f32 v[2:3], v[2:3], v[12:13]
	v_pk_mul_f32 v[0:1], v[0:1], v[10:11]
	v_pk_mul_f32 v[10:11], v[48:49], v[8:9] op_sel_hi:[1,0]
	v_cvt_pk_bf16_f32 v0, v0, v1
	v_cvt_pk_bf16_f32 v1, v2, v3
	global_store_dwordx2 v[6:7], v[0:1], off offset:1024
	s_nop 1
	v_mov_b64_e32 v[0:1], v[212:213]
	v_mov_b64_e32 v[2:3], v[214:215]
	v_pk_mul_f32 v[8:9], v[50:51], v[8:9] op_sel_hi:[1,0]
	s_nop 1
	v_pk_mul_f32 v[0:1], v[0:1], v[10:11]
	v_pk_mul_f32 v[2:3], v[2:3], v[8:9]
	v_cvt_pk_bf16_f32 v0, v0, v1
	v_cvt_pk_bf16_f32 v1, v2, v3
	global_store_dwordx2 v[6:7], v[0:1], off offset:1536
	s_nop 1
	v_mov_b64_e32 v[0:1], v[200:201]
	v_mov_b64_e32 v[2:3], v[202:203]
	v_rsq_f32_e32 v6, v4
	v_lshl_add_u64 v[4:5], v[60:61], 0, s[10:11]
	v_mul_f32_e32 v7, 0x45800000, v6
	v_cndmask_b32_e32 v6, v6, v7, vcc
	v_pk_mul_f32 v[8:9], v[44:45], v[6:7] op_sel_hi:[1,0]
	v_pk_mul_f32 v[10:11], v[46:47], v[6:7] op_sel_hi:[1,0]
	s_nop 1
	v_pk_mul_f32 v[0:1], v[0:1], v[8:9]
	v_pk_mul_f32 v[2:3], v[2:3], v[10:11]
	v_cvt_pk_bf16_f32 v0, v0, v1
	v_cvt_pk_bf16_f32 v1, v2, v3
	global_store_dwordx2 v[4:5], v[0:1], off
	s_nop 1
	v_mov_b64_e32 v[0:1], v[204:205]
	v_mov_b64_e32 v[2:3], v[206:207]
	v_pk_mul_f32 v[8:9], v[40:41], v[6:7] op_sel_hi:[1,0]
	v_pk_mul_f32 v[10:11], v[42:43], v[6:7] op_sel_hi:[1,0]
	s_nop 1
	v_pk_mul_f32 v[0:1], v[0:1], v[8:9]
	v_pk_mul_f32 v[2:3], v[2:3], v[10:11]
	v_cvt_pk_bf16_f32 v0, v0, v1
	v_cvt_pk_bf16_f32 v1, v2, v3
	global_store_dwordx2 v[4:5], v[0:1], off offset:512
	s_nop 1
	v_mov_b64_e32 v[0:1], v[208:209]
	v_mov_b64_e32 v[2:3], v[210:211]
	v_pk_mul_f32 v[8:9], v[36:37], v[6:7] op_sel_hi:[1,0]
	v_pk_mul_f32 v[10:11], v[38:39], v[6:7] op_sel_hi:[1,0]
	s_nop 1
	v_pk_mul_f32 v[0:1], v[0:1], v[8:9]
	v_pk_mul_f32 v[2:3], v[2:3], v[10:11]
	v_cvt_pk_bf16_f32 v0, v0, v1
	v_cvt_pk_bf16_f32 v1, v2, v3
	global_store_dwordx2 v[4:5], v[0:1], off offset:1024
	s_nop 1
	v_mov_b64_e32 v[0:1], v[212:213]
	v_mov_b64_e32 v[2:3], v[214:215]
	v_pk_mul_f32 v[8:9], v[24:25], v[6:7] op_sel_hi:[1,0]
	v_pk_mul_f32 v[6:7], v[26:27], v[6:7] op_sel_hi:[1,0]
	s_nop 1
	v_pk_mul_f32 v[0:1], v[0:1], v[8:9]
	v_pk_mul_f32 v[2:3], v[2:3], v[6:7]
	v_cvt_pk_bf16_f32 v0, v0, v1
	v_cvt_pk_bf16_f32 v1, v2, v3
	global_store_dwordx2 v[4:5], v[0:1], off offset:1536
	s_cbranch_scc1 .LBB0_232

; #define LAS __attribute__((address_space(3)))
; DI void conv_row(const bf16* qkv, int row0, int n, int coff, const float* cw, LAS unsigned char* R, LAS unsigned char* HX, int lane, float (&y)[64]) {
;     const __attribute__((address_space(4))) float* cw4 = (const __attribute__((address_space(4))) float*)(uintptr_t)cw;
; #pragma unroll
;     for (int it = 0; it < 8; ++it) { const int r = it * 8 + (lane >> 3), c8 = lane & 7;
;         const u32x4 v = __builtin_nontemporal_load((const u32x4*)(qkv + (size_t)(row0 + r) * 1536 + coff + c8 * 8)); *(LAS u32x4*)(R + r * 144 + c8 * 16) = v; }
;     {
;         const int hr = lane >> 3, c8 = lane & 7;
;         u32x4 v = {0u, 0u, 0u, 0u};
;         if (lane < 24 && n > 0) v = *(const u32x4*)(qkv + (size_t)(row0 - 3 + hr) * 1536 + coff + c8 * 8);
;         if (lane < 24) *(LAS u32x4*)(HX + hr * 144 + c8 * 16) = v;
.LBB0_625:
	s_cmp_lg_u32 s70, 3
	s_cselect_b64 s[68:69], -1, 0
	s_cmp_eq_u32 s70, 2
	s_cselect_b32 s12, 0x200, 0
	s_cmp_eq_u32 s70, 3
	s_cselect_b64 s[30:31], -1, 0
	s_and_b64 s[10:11], s[30:31], exec
	s_cselect_b32 s10, 0x400, s12
	s_or_b32 s15, s10, s71
	s_cmp_lg_u32 s70, 1
	s_cselect_b64 s[34:35], -1, 0
	s_cmp_eq_u32 s70, 1
	s_cselect_b64 s[10:11], -1, 0
	s_and_b64 s[12:13], s[10:11], exec
	s_cselect_b32 s14, s97, s95
	s_lshl_b32 s76, s15, 1
	v_lshl_add_u64 v[4:5], v[60:61], 0, s[76:77]
	v_lshl_add_u64 v[0:1], v[4:5], 0, v[62:63]
	global_load_dwordx4 v[0:3], v[0:1], off nt
	v_lshl_add_u64 v[12:13], v[4:5], 0, v[64:65]
	global_load_dwordx4 v[12:15], v[12:13], off nt
	v_lshl_add_u64 v[16:17], v[4:5], 0, v[66:67]
	global_load_dwordx4 v[16:19], v[16:17], off nt
	v_lshl_add_u64 v[20:21], v[4:5], 0, v[68:69]
	global_load_dwordx4 v[20:23], v[20:21], off nt
	v_lshl_add_u64 v[24:25], v[4:5], 0, v[70:71]
	global_load_dwordx4 v[24:27], v[24:25], off nt
	v_lshl_add_u64 v[28:29], v[4:5], 0, v[72:73]
	global_load_dwordx4 v[28:31], v[28:29], off nt
	v_lshl_add_u64 v[32:33], v[4:5], 0, v[74:75]
	global_load_dwordx4 v[32:35], v[32:33], off nt
	v_lshl_add_u64 v[36:37], v[4:5], 0, v[76:77]
	global_load_dwordx4 v[36:39], v[36:37], off nt
	v_add_u32_e32 v6, s14, v80
	v_add_u32_e32 v172, v6, v83
	s_waitcnt vmcnt(7)
	ds_write_b128 v172, v[0:3]
	s_waitcnt vmcnt(6)
	ds_write_b128 v172, v[12:15] offset:1152
	s_waitcnt vmcnt(5)
	ds_write_b128 v172, v[16:19] offset:2304
	s_waitcnt vmcnt(4)
	ds_write_b128 v172, v[20:23] offset:3456
	s_waitcnt vmcnt(3)
	ds_write_b128 v172, v[24:27] offset:4608
	s_waitcnt vmcnt(2)
	ds_write_b128 v172, v[28:31] offset:5760
	s_waitcnt vmcnt(1)
	ds_write_b128 v172, v[32:35] offset:6912
	s_waitcnt vmcnt(0)
	ds_write_b128 v172, v[36:39] offset:8064
	v_mov_b32_e32 v0, 0
	v_mov_b32_e32 v1, 0
	v_mov_b32_e32 v2, 0
	v_mov_b32_e32 v3, 0
	s_and_saveexec_b64 s[12:13], s[28:29]
	s_cbranch_execz .LBB0_627
	v_lshl_add_u64 v[0:1], v[78:79], 0, s[76:77]
	global_load_dwordx4 v[0:3], v[0:1], off
